# v16 + retention scan writes its states in place over KVC (same addresses: 33 MB less live footprint in the infinity cache); P4 reads them there
# baseline (speedup 1.0000x reference)
; __device__ __forceinline__ float log_sigmoid(float x) { return -log1pf(expf(-x)); }
; __global__ void __launch_bounds__(512, 2) fwd_mega(Args a) {
;     ...
;             const int p = idx & 8191, bh = (idx >> 13) & 7, dir = idx >> 16, h = bh & 3;
;             const float lg = log_sigmoid(dir ? a.in[6][h] : a.in[5][h]); const float dec = expf(lg * 128.f);
;             const size_t base = (size_t)(dir * 8 + bh) * 64 * 16384 + (size_t)p * 2;
;             const bf16* kv = KVC + base; bf16* st = ST + base;
;             float s0 = 0.f, s1 = 0.f;
;             const unsigned* kvw = (const unsigned*)kv; unsigned* stw = (unsigned*)st;
.LBB0_377:
	v_cmp_gt_u32_e32 vcc, s26, v26
	v_lshrrev_b32_e32 v0, 11, v26
	v_and_b32_e32 v0, 12, v0
	v_cndmask_b32_e32 v3, v27, v28, vcc
	v_cndmask_b32_e32 v2, v29, v30, vcc
	v_lshl_add_u64 v[2:3], v[2:3], 0, v[0:1]
	global_load_dword v0, v[2:3], off nt
	v_lshrrev_b32_e32 v3, 13, v26
	v_ashrrev_i32_e32 v4, 13, v26
	v_bfi_b32 v4, -8, v4, v3
	v_lshlrev_b32_e32 v8, 2, v26
	v_readlane_b32 s44, v255, 10
	v_readlane_b32 s58, v255, 24
	v_readlane_b32 s59, v255, 25
	s_mov_b32 s42, 0
	s_mov_b32 s43, 63
	v_mov_b32_e32 v2, v1
	v_readlane_b32 s45, v255, 11
	v_readlane_b32 s46, v255, 12
	v_readlane_b32 s47, v255, 13
	v_readlane_b32 s48, v255, 14
	v_readlane_b32 s49, v255, 15
	v_readlane_b32 s50, v255, 16
	v_readlane_b32 s51, v255, 17
	v_readlane_b32 s52, v255, 18
	v_readlane_b32 s53, v255, 19
	v_readlane_b32 s54, v255, 20
	v_readlane_b32 s55, v255, 21
	v_readlane_b32 s56, v255, 22
	v_readlane_b32 s57, v255, 23
	s_waitcnt vmcnt(0)
	v_mul_f32_e32 v5, 0xbfb8aa3b, v0
	v_fma_f32 v6, v0, s27, -v5
	v_rndne_f32_e32 v7, v5
	v_fmac_f32_e32 v6, 0xb2a5705f, v0
	v_sub_f32_e32 v5, v5, v7
	v_add_f32_e32 v5, v5, v6
	v_cvt_i32_f32_e32 v9, v7
	v_exp_f32_e32 v10, v5
	v_cmp_nlt_f32_e64 s[0:1], s28, v0
	v_ashrrev_i32_e32 v5, 31, v4
	v_lshlrev_b64 v[6:7], 21, v[4:5]
	v_ldexp_f32 v3, v10, v9
	v_cndmask_b32_e64 v3, 0, v3, s[0:1]
	v_cmp_ngt_f32_e64 s[0:1], s29, v0
	v_and_or_b32 v6, v8, s40, v6
	s_nop 0
	v_cndmask_b32_e64 v0, v31, v3, s[0:1]
	v_add_f32_e32 v3, 1.0, v0
	v_add_f32_e32 v9, -1.0, v3
	v_frexp_mant_f32_e32 v10, v3
	v_cvt_f64_f32_e32 v[4:5], v3
	v_sub_f32_e32 v11, v9, v3
	v_frexp_exp_i32_f64_e32 v4, v[4:5]
	v_cmp_gt_f32_e64 s[0:1], s31, v10
	v_sub_f32_e32 v9, v0, v9
	v_add_f32_e32 v5, 1.0, v11
	v_subbrev_co_u32_e64 v4, s[0:1], 0, v4, s[0:1]
	v_add_f32_e32 v5, v9, v5
	v_sub_u32_e32 v9, 0, v4
	v_cvt_f32_i32_e32 v4, v4
	v_ldexp_f32 v3, v3, v9
	v_ldexp_f32 v5, v5, v9
	v_add_f32_e32 v9, -1.0, v3
	v_add_f32_e32 v10, 1.0, v3
	v_add_f32_e32 v11, 1.0, v9
	v_add_f32_e32 v12, -1.0, v10
	v_sub_f32_e32 v11, v3, v11
	v_sub_f32_e32 v3, v3, v12
	v_mul_f32_e32 v12, 0x3f317218, v4
	v_add_f32_e32 v11, v5, v11
	v_add_f32_e32 v3, v5, v3
	v_fma_f32 v5, v4, s33, -v12
	v_add_f32_e32 v13, v9, v11
	v_add_f32_e32 v14, v10, v3
	v_fmac_f32_e32 v5, 0xb102e308, v4
	v_sub_f32_e32 v4, v9, v13
	v_sub_f32_e32 v9, v10, v14
	v_rcp_f32_e32 v10, v14
	v_add_f32_e32 v15, v12, v5
	v_add_f32_e32 v3, v3, v9
	v_sub_f32_e32 v9, v15, v12
	v_sub_f32_e32 v5, v5, v9
	v_mul_f32_e32 v9, v13, v10
	v_add_f32_e32 v4, v11, v4
	v_mul_f32_e32 v11, v14, v9
	v_fma_f32 v12, v9, v14, -v11
	v_fmac_f32_e32 v12, v9, v3
	v_add_f32_e32 v16, v11, v12
	v_sub_f32_e32 v17, v13, v16
	v_sub_f32_e32 v11, v16, v11
	v_sub_f32_e32 v13, v13, v17
	v_sub_f32_e32 v11, v11, v12
	v_sub_f32_e32 v12, v13, v16
	v_add_f32_e32 v4, v4, v12
	v_add_f32_e32 v4, v11, v4
	v_add_f32_e32 v11, v17, v4
	v_mul_f32_e32 v12, v10, v11
	v_sub_f32_e32 v13, v17, v11
	v_mul_f32_e32 v16, v14, v12
	v_add_f32_e32 v4, v4, v13
	v_add_f32_e32 v13, v9, v12
	v_fma_f32 v14, v12, v14, -v16
	v_sub_f32_e32 v9, v13, v9
	v_fmac_f32_e32 v14, v12, v3
	v_sub_f32_e32 v3, v12, v9
	v_add_f32_e32 v9, v16, v14
	v_sub_f32_e32 v12, v9, v16
	v_sub_f32_e32 v16, v11, v9
	v_sub_f32_e32 v11, v11, v16
	v_sub_f32_e32 v9, v11, v9
	v_sub_f32_e32 v12, v12, v14
	v_add_f32_e32 v4, v4, v9
	v_add_f32_e32 v4, v12, v4
	v_add_f32_e32 v4, v16, v4
	v_mul_f32_e32 v4, v10, v4
	v_add_f32_e32 v3, v3, v4
	v_add_f32_e32 v4, v13, v3
	v_mul_f32_e32 v9, v4, v4
	v_fmamk_f32 v12, v9, 0x3e9b6dac, v32
	v_sub_f32_e32 v10, v4, v13
	v_ldexp_f32 v11, v4, 1
	v_mul_f32_e32 v4, v4, v9
	v_fmaak_f32 v9, v9, v12, 0x3f2aaada
	v_mul_f32_e32 v4, v4, v9
	v_add_f32_e32 v9, v11, v4
	v_sub_f32_e32 v3, v3, v10
	v_sub_f32_e32 v10, v9, v11
	v_ldexp_f32 v3, v3, 1
	v_sub_f32_e32 v4, v4, v10
	v_add_f32_e32 v3, v3, v4
	v_add_f32_e32 v4, v9, v3
	v_sub_f32_e32 v9, v4, v9
	v_add_f32_e32 v10, v15, v4
	v_sub_f32_e32 v3, v3, v9
	v_sub_f32_e32 v9, v10, v15
	v_sub_f32_e32 v11, v10, v9
	v_sub_f32_e32 v4, v4, v9
	v_add_f32_e32 v9, v5, v3
	v_sub_f32_e32 v11, v15, v11
	v_sub_f32_e32 v12, v9, v5
	v_add_f32_e32 v4, v4, v11
	v_sub_f32_e32 v11, v9, v12
	v_sub_f32_e32 v3, v3, v12
	v_sub_f32_e32 v5, v5, v11
	v_add_f32_e32 v4, v9, v4
	v_add_f32_e32 v3, v3, v5
	v_add_f32_e32 v5, v10, v4
	v_sub_f32_e32 v9, v5, v10
	v_sub_f32_e32 v4, v4, v9
	v_add_f32_e32 v3, v3, v4
	v_add_f32_e32 v3, v5, v3
	v_cmp_neq_f32_e64 s[0:1], s30, v0
	s_nop 1
	v_cndmask_b32_e64 v3, v31, v3, s[0:1]
	v_cmp_lt_f32_e64 s[0:1], |v0|, s34
	s_nop 1
	v_cndmask_b32_e64 v0, v3, v0, s[0:1]
	v_mul_f32_e32 v0, 0xc3000000, v0
	v_mul_f32_e32 v3, 0x3fb8aa3b, v0
	v_fma_f32 v4, v0, s35, -v3
	v_rndne_f32_e32 v5, v3
	v_fmac_f32_e32 v4, 0x32a5705f, v0
	v_sub_f32_e32 v3, v3, v5
	v_add_f32_e32 v3, v3, v4
	v_cvt_i32_f32_e32 v9, v5
	v_exp_f32_e32 v3, v3
	v_readlane_b32 s0, v255, 26
	v_readlane_b32 s1, v255, 27
	v_ldexp_f32 v3, v3, v9
	s_nop 0
	v_lshl_add_u64 v[4:5], s[0:1], 0, v[6:7]
	v_cmp_ngt_f32_e64 s[0:1], s38, v0
	v_mov_b64_e32 v[6:7], v[4:5]
	s_nop 0
	v_cndmask_b32_e64 v3, 0, v3, s[0:1]
	v_cmp_nlt_f32_e64 s[0:1], s39, v0
	s_nop 1
	v_cndmask_b32_e64 v8, v31, v3, s[0:1]
	v_mov_b32_e32 v9, v8
	v_mov_b32_e32 v3, v1

; #define LAS __attribute__((address_space(3)))
; __device__ __forceinline__ void ret_unit(LAS unsigned char* lds, int u, const bf16* PROJ, const int* pos, const float* dec_f, const float* dec_b, const bf16* ST,
;                                          const float* gn_w, const float* gn_b, bf16* MIX, int tid, const WsRef& wsr) {
;     ...
;     for (int ii = 0; ii < 2; ++ii) { const int it = tid + 512 * ii, dc = it & 7, j = it >> 3; const unsigned qo = (unsigned)WS_PROJ + (unsigned)(((unsigned)(row0 + j) * INC + h * 128 + dc * 8) * 2u);
;         rq1[ii] = ws_load16(wsr, qo); rq2[ii] = ws_load16(wsr, qo + 128u); rk1[ii] = ws_load16(wsr, qo + 1024u); rk2[ii] = ws_load16(wsr, qo + 1152u); rp[ii] = (float)pos[row0 + j]; }
; #pragma unroll
;     for (int ii = 0; ii < 2; ++ii) { const int it = tid + 512 * ii, dc = it & 7, j = it >> 3;
;         const u32x4 q1 = rq1[ii], q2 = rq2[ii], k1 = rk1[ii], k2 = rk2[ii];
;         const float p = rp[ii];
;         float sn[8], cs[8];
; #pragma unroll
;         for (int e = 0; e < 8; ++e) { const int i = dc * 8 + e; const float inv = fexp2(-(float)i * 0.20762050593046015f); fast_sincos(p * inv, sn[e], cs[e]); }
;         u32x4 oq1, oq2, ok1, ok2;
; #pragma unroll
;         for (int e = 0; e < 4; ++e) { const int e0 = 2 * e, e1 = 2 * e + 1;
;             const float a0 = bflo(q1[e]), a1 = bfhi(q1[e]), b0 = bflo(q2[e]), b1 = bfhi(q2[e]);
;             oq1[e] = pk2(a0 * cs[e0] - b0 * sn[e0], a1 * cs[e1] - b1 * sn[e1]); oq2[e] = pk2(b0 * cs[e0] + a0 * sn[e0], b1 * cs[e1] + a1 * sn[e1]);
;             const float c0 = bflo(k1[e]) * 0.08838834764831845f, c1 = bfhi(k1[e]) * 0.08838834764831845f, d0 = bflo(k2[e]) * 0.08838834764831845f, d1 = bfhi(k2[e]) * 0.08838834764831845f;
;             ok1[e] = pk2(c0 * cs[e0] - d0 * sn[e0], c1 * cs[e1] - d1 * sn[e1]); ok2[e] = pk2(d0 * cs[e0] + c0 * sn[e0], d1 * cs[e1] + c1 * sn[e1]); }
;         *(LAS u32x4*)(Qs + j * LDT + dc * 8) = oq1; *(LAS u32x4*)(Qs + j * LDT + 64 + dc * 8) = oq2;
;         *(LAS u32x4*)(Ks + j * LDT + dc * 8) = ok1; *(LAS u32x4*)(Ks + j * LDT + 64 + dc * 8) = ok2; }
; #pragma unroll
;     for (int ii = 0; ii < 4; ++ii) { const int it = tid + 512 * ii, ec = it & 15, j = it >> 4; rv[ii] = ws_load16(wsr, (unsigned)WS_PROJ + (unsigned)(((unsigned)(row0 + j) * INC + 1024 + h * 128 + ec * 8) * 2u)); }
; #pragma unroll
.LBB0_435:
	s_cmp_lt_i32 s86, 5
	s_cselect_b64 s[4:5], -1, 0
	s_and_b64 s[4:5], s[4:5], s[0:1]
	s_andn2_b64 vcc, exec, s[4:5]
	s_cbranch_vccnz .LBB0_440
	s_cmpk_gt_i32 s2, 0x1ff
	s_cbranch_scc1 .LBB0_440
	v_and_b32_e32 v6, 7, v128
	v_lshlrev_b32_e32 v7, 3, v6
	v_cvt_f32_ubyte0_e32 v8, v7
	v_mul_f32_e32 v8, 0xbe549a78, v8
	v_exp_f32_e32 v107, v8
	v_or_b32_e32 v8, 1, v7
	v_cvt_f32_ubyte0_e32 v8, v8
	v_mul_f32_e32 v8, 0xbe549a78, v8
	v_exp_f32_e32 v108, v8
	v_or_b32_e32 v8, 2, v7
	v_cvt_f32_ubyte0_e32 v8, v8
	v_mul_f32_e32 v8, 0xbe549a78, v8
	v_exp_f32_e32 v109, v8
	v_or_b32_e32 v8, 3, v7
	v_cvt_f32_ubyte0_e32 v8, v8
	v_mul_f32_e32 v8, 0xbe549a78, v8
	v_exp_f32_e32 v110, v8
	v_or_b32_e32 v8, 4, v7
	v_cvt_f32_ubyte0_e32 v8, v8
	v_mul_f32_e32 v8, 0xbe549a78, v8
	v_exp_f32_e32 v111, v8
	v_or_b32_e32 v8, 5, v7
	v_cvt_f32_ubyte0_e32 v8, v8
	v_mul_f32_e32 v8, 0xbe549a78, v8
	v_exp_f32_e32 v112, v8
	v_or_b32_e32 v8, 6, v7
	v_or_b32_e32 v7, 7, v7
	v_cvt_f32_ubyte0_e32 v7, v7
	v_lshrrev_b32_e32 v98, 3, v128
	v_mul_f32_e32 v7, 0xbe549a78, v7
	v_add_u32_e32 v1, 0x200, v128
	v_exp_f32_e32 v114, v7
	v_mul_u32_u24_e32 v7, 0x88, v98
	v_lshrrev_b32_e32 v100, 3, v1
	v_lshlrev_b32_e32 v7, 1, v7
	v_lshlrev_b32_e32 v6, 4, v6
	v_cvt_f32_ubyte0_e32 v8, v8
	v_add3_u32 v115, 0, v7, v6
	v_mul_u32_u24_e32 v7, 0x88, v100
	v_lshlrev_b32_e32 v4, 3, v128
	v_mul_f32_e32 v8, 0xbe549a78, v8
	v_lshlrev_b32_e32 v7, 1, v7
	v_lshrrev_b32_e32 v117, 4, v1
	s_add_i32 s0, 0, 0x11000
	v_lshrrev_b32_e32 v1, 7, v1
	v_and_b32_e32 v106, 56, v4
	v_exp_f32_e32 v113, v8
	v_add3_u32 v116, 0, v7, v6
	v_and_b32_e32 v4, 0x78, v4
	s_movk_i32 s1, 0x110
	v_mov_b32_e32 v7, s0
	v_and_b32_e32 v8, 14, v98
	v_bitop3_b32 v1, v1, v128, 7 bitop3:0x78
	v_or_b32_e32 v0, 0x400, v128
	v_mad_u32_u24 v7, v4, s1, v7
	v_lshl_or_b32 v1, v1, 4, v8
	v_add_u32_e32 v121, v7, v1
	v_lshrrev_b32_e32 v1, 7, v0
	v_bitop3_b32 v1, v1, v128, 7 bitop3:0x78
	v_add_u32_e32 v2, 0x600, v128
	v_lshl_or_b32 v1, v1, 4, v8
	v_add_u32_e32 v122, v7, v1
	v_lshrrev_b32_e32 v1, 7, v2
	v_bitop3_b32 v1, v1, v128, 7 bitop3:0x78
	v_writelane_b32 v255, s4, 38
	v_lshrrev_b32_e32 v6, 7, v128
	v_lshl_or_b32 v1, v1, 4, v8
	v_writelane_b32 v255, s5, 39
	v_and_b32_e32 v3, 15, v128
	v_bfe_u32 v5, v128, 4, 2
	v_bitop3_b32 v6, v6, v128, 7 bitop3:0x78
	v_add_u32_e32 v123, v7, v1
	v_lshrrev_b32_e32 v1, 2, v128
	s_movk_i32 s3, 0xf0
	v_writelane_b32 v255, s82, 40
	v_lshl_or_b32 v6, v6, 4, v8
	v_and_or_b32 v102, v1, s3, v3
	v_lshlrev_b32_e32 v126, 2, v5
	v_writelane_b32 v255, s83, 41
	v_lshrrev_b32_e32 v119, 4, v2
	v_add_u32_e32 v120, v7, v6
	v_lshlrev_b32_e32 v2, 4, v5
	v_mov_b32_e32 v7, 0x5500
	v_sub_u32_e32 v5, v102, v126
	v_writelane_b32 v255, s80, 42
	v_mad_u32_u24 v125, v3, s1, v7
	v_sub_u32_e32 v7, 0, v5
	v_writelane_b32 v255, s81, 43
	v_max_i32_e32 v7, v5, v7
	v_cmp_gt_i32_e64 s[4:5], 0, v5
	v_xad_u32 v5, v126, -1, v102
	v_cvt_f32_u32_e32 v127, v7
	v_writelane_b32 v255, s4, 44
	v_sub_u32_e32 v7, 0, v5
	v_max_i32_e32 v7, v5, v7
	v_writelane_b32 v255, s5, 45
	v_cmp_gt_i32_e64 s[4:5], 0, v5
	v_or_b32_e32 v5, 2, v126
	v_sub_u32_e32 v5, v102, v5
	v_writelane_b32 v255, s4, 46
	v_cvt_f32_u32_e32 v129, v7
	v_sub_u32_e32 v7, 0, v5
	v_writelane_b32 v255, s5, 47
	v_max_i32_e32 v7, v5, v7
	v_cmp_gt_i32_e64 s[4:5], 0, v5
	v_or_b32_e32 v5, 3, v126
	v_sub_u32_e32 v5, v102, v5
	v_cvt_f32_u32_e32 v231, v7
	v_sub_u32_e32 v7, 0, v5
	v_max_i32_e32 v7, v5, v7
	v_cmp_gt_i32_e64 s[82:83], 0, v5
	v_or_b32_e32 v5, 16, v126
	v_sub_u32_e32 v5, v102, v5
	v_cvt_f32_u32_e32 v252, v7
	v_sub_u32_e32 v7, 0, v5
	v_max_i32_e32 v7, v5, v7
	v_cmp_gt_i32_e64 s[80:81], 0, v5
	v_or_b32_e32 v5, 17, v126
	v_sub_u32_e32 v5, v102, v5
	v_writelane_b32 v255, s4, 48
	v_cvt_f32_u32_e32 v253, v7
	v_sub_u32_e32 v7, 0, v5
	v_writelane_b32 v255, s5, 49
	v_max_i32_e32 v7, v5, v7
	v_cmp_gt_i32_e64 s[4:5], 0, v5
	v_or_b32_e32 v5, 18, v126
	v_sub_u32_e32 v5, v102, v5
	v_cvt_f32_u32_e32 v254, v7
	v_sub_u32_e32 v7, 0, v5
	v_max_i32_e32 v7, v5, v7
	v_cmp_gt_i32_e64 s[66:67], 0, v5
	v_or_b32_e32 v5, 19, v126
	v_sub_u32_e32 v5, v102, v5
	v_cvt_f32_u32_e32 v134, v7
	v_sub_u32_e32 v7, 0, v5
	v_max_i32_e32 v7, v5, v7
	v_cmp_gt_i32_e64 s[26:27], 0, v5
	v_or_b32_e32 v5, 32, v126
	v_sub_u32_e32 v5, v102, v5
	v_cvt_f32_u32_e32 v135, v7
	v_sub_u32_e32 v7, 0, v5
	v_max_i32_e32 v7, v5, v7
	v_cmp_gt_i32_e64 s[28:29], 0, v5
	v_or_b32_e32 v5, 33, v126
	v_sub_u32_e32 v5, v102, v5
	v_cvt_f32_u32_e32 v136, v7
	v_sub_u32_e32 v7, 0, v5
	v_max_i32_e32 v7, v5, v7
	v_cmp_gt_i32_e64 s[30:31], 0, v5
	v_or_b32_e32 v5, 34, v126
	v_sub_u32_e32 v5, v102, v5
	v_cvt_f32_u32_e32 v137, v7
	v_sub_u32_e32 v7, 0, v5
	v_max_i32_e32 v7, v5, v7
	v_cmp_gt_i32_e64 s[34:35], 0, v5
	v_or_b32_e32 v5, 35, v126
	v_sub_u32_e32 v5, v102, v5
	v_cvt_f32_u32_e32 v138, v7
	v_sub_u32_e32 v7, 0, v5
	v_max_i32_e32 v7, v5, v7
	v_cmp_gt_i32_e64 s[38:39], 0, v5
	v_or_b32_e32 v5, 48, v126
	v_sub_u32_e32 v5, v102, v5
	v_cvt_f32_u32_e32 v139, v7
	v_sub_u32_e32 v7, 0, v5
	v_max_i32_e32 v7, v5, v7
	v_cmp_gt_i32_e64 s[74:75], 0, v5
	v_or_b32_e32 v5, 49, v126
	v_sub_u32_e32 v5, v102, v5
	v_cvt_f32_u32_e32 v140, v7
	v_sub_u32_e32 v7, 0, v5
	v_max_i32_e32 v7, v5, v7
	v_cmp_gt_i32_e64 s[76:77], 0, v5
	v_or_b32_e32 v5, 50, v126
	v_sub_u32_e32 v5, v102, v5
	v_cvt_f32_u32_e32 v141, v7
	v_sub_u32_e32 v7, 0, v5
	v_max_i32_e32 v7, v5, v7
	v_cmp_gt_i32_e64 s[56:57], 0, v5
	v_or_b32_e32 v5, 51, v126
	v_sub_u32_e32 v5, v102, v5
	v_cvt_f32_u32_e32 v142, v7
	v_sub_u32_e32 v7, 0, v5
	v_max_i32_e32 v7, v5, v7
	v_cmp_gt_i32_e64 s[58:59], 0, v5
	v_or_b32_e32 v5, 64, v126
	v_sub_u32_e32 v5, v102, v5
	v_cvt_f32_u32_e32 v143, v7
	v_sub_u32_e32 v7, 0, v5
	v_max_i32_e32 v7, v5, v7
; __device__ __forceinline__ float fexp2(float x) { return __builtin_amdgcn_exp2f(x); }
; __device__ __forceinline__ void ret_unit(LAS unsigned char* lds, int u, const bf16* PROJ, const int* pos, const float* dec_f, const float* dec_b, const bf16* ST,
;                                          const float* gn_w, const float* gn_b, bf16* MIX, int tid, const WsRef& wsr) {
;     ...
; #pragma unroll
;     for (int n = 0; n < 8; ++n) {
; #pragma unroll
;         for (int r = 0; r < 4; ++r) { const int key = n * 16 + 4 * fq + r; const int df = q - key; const float f = df >= 0 ? fexp2(lgf2 * (float)df) : fexp2(lgb2 * (float)(-df)); s[n][r] *= f; } }
	v_cmp_gt_i32_e64 s[60:61], 0, v5
	v_or_b32_e32 v5, 0x41, v126
	v_sub_u32_e32 v5, v102, v5
	v_cvt_f32_u32_e32 v144, v7
	v_sub_u32_e32 v7, 0, v5
	v_max_i32_e32 v7, v5, v7
	v_cmp_gt_i32_e64 s[62:63], 0, v5
	v_or_b32_e32 v5, 0x42, v126
	v_sub_u32_e32 v5, v102, v5
	v_cvt_f32_u32_e32 v145, v7
	v_sub_u32_e32 v7, 0, v5
	v_max_i32_e32 v7, v5, v7
	v_cmp_gt_i32_e64 s[64:65], 0, v5
	v_or_b32_e32 v5, 0x43, v126
	v_sub_u32_e32 v5, v102, v5
	v_cvt_f32_u32_e32 v146, v7
	v_sub_u32_e32 v7, 0, v5
	v_max_i32_e32 v7, v5, v7
	v_cmp_gt_i32_e64 s[14:15], 0, v5
	v_or_b32_e32 v5, 0x50, v126
	v_sub_u32_e32 v5, v102, v5
	v_cvt_f32_u32_e32 v147, v7
	v_sub_u32_e32 v7, 0, v5
	v_max_i32_e32 v7, v5, v7
	v_cmp_gt_i32_e64 s[16:17], 0, v5
	v_or_b32_e32 v5, 0x51, v126
	v_sub_u32_e32 v5, v102, v5
	v_cvt_f32_u32_e32 v148, v7
	v_sub_u32_e32 v7, 0, v5
	v_max_i32_e32 v7, v5, v7
	v_cmp_gt_i32_e64 s[24:25], 0, v5
	v_or_b32_e32 v5, 0x52, v126
	v_sub_u32_e32 v5, v102, v5
	v_cvt_f32_u32_e32 v149, v7
	v_sub_u32_e32 v7, 0, v5
	v_max_i32_e32 v7, v5, v7
	v_cmp_gt_i32_e64 s[78:79], 0, v5
	v_or_b32_e32 v5, 0x53, v126
	v_sub_u32_e32 v5, v102, v5
	v_cvt_f32_u32_e32 v150, v7
	v_sub_u32_e32 v7, 0, v5
	s_mov_b32 s73, s2
	v_max_i32_e32 v7, v5, v7
	v_cmp_gt_i32_e64 s[2:3], 0, v5
	v_or_b32_e32 v5, 0x60, v126
	v_sub_u32_e32 v5, v102, v5
	v_cvt_f32_u32_e32 v151, v7
	v_sub_u32_e32 v7, 0, v5
	v_max_i32_e32 v7, v5, v7
	v_cmp_gt_i32_e64 s[92:93], 0, v5
	v_or_b32_e32 v5, 0x61, v126
	v_sub_u32_e32 v5, v102, v5
	v_cvt_f32_u32_e32 v152, v7
	v_sub_u32_e32 v7, 0, v5
	v_max_i32_e32 v7, v5, v7
	v_cmp_gt_i32_e32 vcc, 0, v5
	v_or_b32_e32 v5, 0x62, v126
	v_sub_u32_e32 v5, v102, v5
	v_cvt_f32_u32_e32 v153, v7
	v_sub_u32_e32 v7, 0, v5
	v_max_i32_e32 v7, v5, v7
	v_cmp_gt_i32_e64 s[94:95], 0, v5
	v_or_b32_e32 v5, 0x63, v126
	v_sub_u32_e32 v5, v102, v5
	v_cvt_f32_u32_e32 v154, v7
	v_sub_u32_e32 v7, 0, v5
	v_max_i32_e32 v7, v5, v7
	v_cmp_gt_i32_e64 s[8:9], 0, v5
	v_or_b32_e32 v5, 0x70, v126
	v_sub_u32_e32 v5, v102, v5
	v_writelane_b32 v255, s8, 4
	v_cvt_f32_u32_e32 v155, v7
	v_sub_u32_e32 v7, 0, v5
	v_writelane_b32 v255, s9, 5
	v_max_i32_e32 v7, v5, v7
	v_cmp_gt_i32_e64 s[8:9], 0, v5
	v_or_b32_e32 v5, 0x71, v126
	v_sub_u32_e32 v5, v102, v5
	v_writelane_b32 v255, s8, 50
	v_cvt_f32_u32_e32 v156, v7
	v_sub_u32_e32 v7, 0, v5
	v_writelane_b32 v255, s9, 51
	v_max_i32_e32 v7, v5, v7
	v_cmp_gt_i32_e64 s[8:9], 0, v5
	v_or_b32_e32 v5, 0x72, v126
	v_sub_u32_e32 v5, v102, v5
	v_writelane_b32 v255, s8, 52
	v_cvt_f32_u32_e32 v157, v7
	v_sub_u32_e32 v7, 0, v5
	v_writelane_b32 v255, s9, 53
	v_max_i32_e32 v7, v5, v7
	v_cmp_gt_i32_e64 s[8:9], 0, v5
	v_or_b32_e32 v5, 0x73, v126
	v_sub_u32_e32 v5, v102, v5
	v_cvt_f32_u32_e32 v158, v7
	v_sub_u32_e32 v7, 0, v5
	v_lshrrev_b32_e32 v99, 4, v128
	v_writelane_b32 v255, s8, 54
	v_max_i32_e32 v7, v5, v7
	v_lshrrev_b32_e32 v8, 1, v128
	v_writelane_b32 v255, s9, 55
	v_cmp_gt_i32_e64 s[8:9], 0, v5
	v_cvt_f32_u32_e32 v159, v7
	v_bfe_u32 v5, v128, 3, 1
	v_bfe_u32 v7, v99, 1, 1
	v_and_b32_e32 v8, 8, v8
	v_add_u32_e32 v8, s0, v8
	v_xor_b32_e32 v9, v7, v5
	v_mad_u32_u24 v160, v3, s1, v8
	v_lshlrev_b32_e32 v161, 4, v9
	v_bitop3_b32 v9, v7, v5, 2 bitop3:0x36
	v_add_u32_e32 v173, v8, v125
	v_bitop3_b32 v8, v7, v5, 4 bitop3:0x36
	v_lshlrev_b32_e32 v162, 4, v9
	v_or_b32_e32 v9, 2, v5
	v_bitop3_b32 v10, v5, v7, 2 bitop3:0x36
	v_lshlrev_b32_e32 v176, 4, v8
	v_bitop3_b32 v8, v7, v5, 6 bitop3:0x36
	v_lshlrev_b32_e32 v164, 4, v10
	v_bitop3_b32 v10, v7, v5, 2 bitop3:0x14
	v_lshlrev_b32_e32 v177, 4, v8
	v_bitop3_b32 v8, v7, v9, 4 bitop3:0x36
	v_lshlrev_b32_e32 v165, 4, v10
	v_or_b32_e32 v10, 4, v5
	v_bitop3_b32 v11, v5, v7, 4 bitop3:0x36
	v_lshlrev_b32_e32 v178, 4, v8
	v_bitop3_b32 v8, v7, v9, 6 bitop3:0x36
	v_lshlrev_b32_e32 v167, 4, v11
	v_bitop3_b32 v11, v7, v10, 2 bitop3:0x36
	v_lshlrev_b32_e32 v179, 4, v8
	v_bitop3_b32 v8, v7, v5, 4 bitop3:0x14
	v_lshlrev_b32_e32 v168, 4, v11
	v_or_b32_e32 v11, 6, v5
	v_lshlrev_b32_e32 v180, 4, v8
	v_bitop3_b32 v8, v7, v10, 6 bitop3:0x36
	v_lshlrev_b32_e32 v181, 4, v8
	v_bitop3_b32 v8, v7, v11, 4 bitop3:0x36
	v_lshlrev_b32_e32 v182, 4, v8
	v_bitop3_b32 v8, v7, v5, 6 bitop3:0x14
	v_lshlrev_b32_e32 v183, 4, v8
	v_bitop3_b32 v8, v7, v5, 8 bitop3:0x36
	v_lshlrev_b32_e32 v184, 4, v8
	v_bitop3_b32 v8, v7, v5, 10 bitop3:0x36
	v_lshlrev_b32_e32 v185, 4, v8
; __device__ __forceinline__ void ret_unit(LAS unsigned char* lds, int u, const bf16* PROJ, const int* pos, const float* dec_f, const float* dec_b, const bf16* ST,
;                                          const float* gn_w, const float* gn_b, bf16* MIX, int tid, const WsRef& wsr) {
;     ...
;     const u32x4* sfp = (const u32x4*)(ST + ((size_t)bh * 64 + c) * 16384); const u32x4* sbp = (const u32x4*)(ST + ((size_t)(8 + bh) * 64 + c) * 16384);
;     ...
;         for (int n = 0; n < 8; ++n) { const int sw = (2 * n + (fr >> 3)) & 7, jc = kk * 4 + (fq >> 1); const LAS bf16* vr = VT + (n * 16 + fr) * LDT + 4 * (fq & 1);
;             const u32x2 lo = *(const LAS u32x2*)(vr + ((jc ^ sw) << 3)), hi = *(const LAS u32x2*)(vr + (((jc + 2) ^ sw) << 3)); u32x4 w; w.x = lo.x; w.y = lo.y; w.z = hi.x; w.w = hi.y;
;             o[n] = MFMA16(__builtin_bit_cast(bf16x8, w), pf[kk], o[n]); }
;     __syncthreads();
; #pragma unroll
;     for (int i = 0; i < 4; ++i) { const int id = tid + 512 * i, e = id >> 4, dch = id & 15;
;         *(LAS u32x4*)(Ks + e * LDT + dch * 8) = sf[i]; *(LAS u32x4*)(VT + e * LDT + dch * 8) = sb[i]; }
;     __syncthreads();
;     {
;         f32x4 tf[8], tb[8];
; #pragma unroll
;         for (int n = 0; n < 8; ++n) { tf[n] = (f32x4){0.f, 0.f, 0.f, 0.f}; tb[n] = (f32x4){0.f, 0.f, 0.f, 0.f}; }
; #pragma unroll
;         for (int kk = 0; kk < 4; ++kk)
; #pragma unroll
;             for (int n = 0; n < 8; ++n) { const bf16x8 yf = *(const LAS bf16x8*)(Ks + (n * 16 + fr) * LDT + kk * 32 + fq * 8); const bf16x8 yb = *(const LAS bf16x8*)(VT + (n * 16 + fr) * LDT + kk * 32 + fq * 8);
;                 tf[n] = MFMA16(yf, qf[kk], tf[n]); tb[n] = MFMA16(yb, qf[kk], tb[n]); }
;         const float xif = fexp2(lgf2 * (float)(q + 1)), xib = fexp2(lgb2 * (float)(128 - q));
; #pragma unroll
;         for (int n = 0; n < 8; ++n) o[n] = o[n] + tf[n] * xif + tb[n] * xib;
;     }
;     float sm = 0.f;
; #pragma unroll
;     for (int n = 0; n < 8; ++n) sm += (o[n][0] + o[n][1]) + (o[n][2] + o[n][3]);
;     sm += __shfl_xor(sm, 16); sm += __shfl_xor(sm, 32);
;     const float mu = sm * (1.f / 128.f);
;     float vq = 0.f;
; #pragma unroll
;     for (int n = 0; n < 8; ++n) { const f32x4 d = o[n] - mu; vq += (d[0] * d[0] + d[1] * d[1]) + (d[2] * d[2] + d[3] * d[3]); }
;     vq += __shfl_xor(vq, 16); vq += __shfl_xor(vq, 32);
;     const float rstd = rsqrtf(vq * (1.f / 128.f) + EPS);
	v_bitop3_b32 v8, v7, v9, 8 bitop3:0x36
	v_lshlrev_b32_e32 v186, 4, v8
	v_bitop3_b32 v8, v7, v9, 10 bitop3:0x36
	v_lshlrev_b32_e32 v187, 4, v8
	v_bitop3_b32 v8, v7, v10, 8 bitop3:0x36
	v_lshlrev_b32_e32 v188, 4, v8
	v_bitop3_b32 v8, v7, v10, 10 bitop3:0x36
	v_lshlrev_b32_e32 v189, 4, v8
	v_bitop3_b32 v8, v7, v11, 8 bitop3:0x36
	v_lshlrev_b32_e32 v190, 4, v8
	v_bitop3_b32 v8, v7, v11, 10 bitop3:0x36
	v_bitop3_b32 v12, v5, v7, 6 bitop3:0x36
	v_lshlrev_b32_e32 v191, 4, v8
	v_bitop3_b32 v8, v7, v5, 12 bitop3:0x36
	v_bitop3_b32 v5, v7, v5, 14 bitop3:0x36
	v_lshlrev_b32_e32 v193, 4, v5
	v_bitop3_b32 v5, v7, v9, 12 bitop3:0x36
	v_lshlrev_b32_e32 v194, 4, v5
	v_bitop3_b32 v5, v7, v9, 14 bitop3:0x36
	v_lshlrev_b32_e32 v195, 4, v5
	v_bitop3_b32 v5, v7, v10, 12 bitop3:0x36
	v_lshlrev_b32_e32 v196, 4, v5
	v_bitop3_b32 v5, v7, v10, 14 bitop3:0x36
	v_lshlrev_b32_e32 v197, 4, v5
	v_bitop3_b32 v5, v7, v11, 12 bitop3:0x36
	v_lshlrev_b32_e32 v198, 4, v5
	v_bitop3_b32 v5, v7, v11, 14 bitop3:0x36
	v_lshlrev_b32_e32 v192, 4, v8
	v_lshlrev_b32_e32 v199, 4, v5
	v_lshlrev_b32_e32 v5, 1, v4
	v_mul_u32_u24_e32 v8, 0x88, v99
	v_lshlrev_b32_e32 v170, 4, v12
	v_bitop3_b32 v12, v7, v11, 2 bitop3:0x36
	v_add_u32_e32 v7, 0, v5
	v_add_u32_e32 v5, s0, v5
	v_lshlrev_b32_e32 v8, 1, v8
	v_mul_u32_u24_e32 v6, 0x110, v3
	v_add_u32_e32 v200, v7, v8
	v_add_u32_e32 v201, v5, v8
	v_mul_u32_u24_e32 v8, 0x88, v117
	v_mul_u32_u24_e32 v3, 0x88, v3
	v_lshrrev_b32_e32 v118, 4, v0
	v_add_u32_e32 v124, 0, v2
	v_lshlrev_b32_e32 v8, 1, v8
	v_lshlrev_b32_e32 v3, 1, v3
	v_add_u32_e32 v202, v7, v8
	v_add_u32_e32 v203, v5, v8
	v_mul_u32_u24_e32 v8, 0x88, v118
	v_add_u32_e32 v209, v124, v3
	v_add3_u32 v210, s0, v2, v3
	v_add_u32_e32 v3, 1, v102
	v_lshlrev_b32_e32 v8, 1, v8
	v_cvt_f32_u32_e32 v218, v3
	v_sub_u32_e32 v3, 0x80, v102
	v_add_u32_e32 v205, v7, v8
	v_add_u32_e32 v206, v5, v8
	v_mul_u32_u24_e32 v8, 0x88, v119
	v_cvt_f32_i32_e32 v219, v3
	v_mbcnt_lo_u32_b32 v3, -1, 0
	v_lshlrev_b32_e32 v8, 1, v8
	v_mbcnt_hi_u32_b32 v3, -1, v3
	v_writelane_b32 v255, s8, 56
	v_add_u32_e32 v207, v7, v8
	v_and_b32_e32 v7, 64, v3
	v_writelane_b32 v255, s9, 57
	v_add_u32_e32 v208, v5, v8
	v_xor_b32_e32 v5, 16, v3
	v_add_u32_e32 v7, 64, v7
	v_cmp_lt_i32_e64 s[68:69], v5, v7
	v_writelane_b32 v255, s73, 58
	v_mov_b32_e32 v97, 0
	v_cndmask_b32_e64 v5, v3, v5, s[68:69]
	v_readlane_b32 s40, v255, 10
	v_lshlrev_b32_e32 v220, 2, v5
	v_xor_b32_e32 v5, 32, v3
	v_readlane_b32 s41, v255, 11
	v_cmp_lt_i32_e64 s[68:69], v5, v7
	v_readlane_b32 s42, v255, 12
	v_readlane_b32 s43, v255, 13
	v_readlane_b32 s44, v255, 14
	v_readlane_b32 s45, v255, 15
	v_readlane_b32 s46, v255, 16
	v_readlane_b32 s47, v255, 17
	v_readlane_b32 s40, v255, 8
	v_mad_u32_u24 v1, v102, s1, 0
	v_cndmask_b32_e64 v3, v3, v5, s[68:69]
	v_readlane_b32 s48, v255, 18
	v_readlane_b32 s49, v255, 19
	v_readlane_b32 s50, v255, 20
	v_readlane_b32 s51, v255, 21
	v_readlane_b32 s52, v255, 22
	v_readlane_b32 s53, v255, 23
	v_readlane_b32 s46, v255, 48
	v_readlane_b32 s44, v255, 46
	v_readlane_b32 s42, v255, 44
	v_readlane_b32 s41, v255, 9
	v_mov_b32_e32 v101, v97
	v_add_u32_e32 v163, 0x1100, v160
	v_add_u32_e32 v166, 0x2200, v160
	v_add_u32_e32 v169, 0x3300, v160
	v_lshlrev_b32_e32 v171, 4, v12
	v_add_u32_e32 v172, 0x4400, v160
	v_add_u32_e32 v174, 0x1100, v173
	v_add_u32_e32 v175, 0x2200, v173
	v_add_u32_e32 v211, 0x1100, v210
	v_add_u32_e32 v212, 0x2200, v210
	v_add_u32_e32 v213, 0x3300, v210
	v_add_u32_e32 v214, 0x4400, v210
	v_add_u32_e32 v215, 0x5500, v210
	v_add_u32_e32 v216, 0x6600, v210
	v_add_u32_e32 v217, 0x7700, v210
	v_mov_b32_e32 v103, v97
	v_lshlrev_b32_e32 v221, 2, v3
	v_or_b32_e32 v222, 0x400, v4
	v_mov_b32_e32 v223, 0x3ecc95a3
	v_lshlrev_b32_e32 v96, 4, v128
	v_lshlrev_b32_e32 v224, 4, v0
	s_movk_i32 s9, 0xc00
	s_mov_b32 s10, 0x3db504f3
	v_add_u32_e32 v225, v1, v2
	v_add_u32_e32 v226, v124, v6
	v_mov_b32_e32 v227, 0x358637bd
	s_movk_i32 s72, 0x1800
	v_mov_b32_e32 v228, 0x7f800000
	v_mov_b32_e32 v104, 0x3f317218
	v_mov_b32_e32 v229, 0x8800000
	v_readlane_b32 s54, v255, 26
	v_readlane_b32 s55, v255, 27
	s_mov_b64 s[50:51], s[80:81]
	s_mov_b64 s[48:49], s[82:83]
	v_readlane_b32 s47, v255, 49
	v_readlane_b32 s45, v255, 47
	v_readlane_b32 s43, v255, 45
	s_mov_b64 s[52:53], s[4:5]
	s_mov_b32 s41, 0xbfb8aa3b
	s_mov_b32 s33, 0x3f317218
	s_mov_b32 s100, 0
